# v048 plus the two inline-asm waits before each K-loop barrier merged into one s_waitcnt vmcnt(8) lgkmcnt(0)
# speedup vs baseline: 1.0070x; 1.0070x over previous
; #define PG8_STAGE(bufoff, gbase, voff) do { _Pragma("unroll") for (int _i = 0; _i < 2; ++_i) \
;         __builtin_amdgcn_global_load_lds((const unsigned*)((const char*)(gbase) + (voff)[_i]), (PG8_LAS unsigned*)(lds + (bufoff) + ldsw + _i * 8192), 16, 0, 0); } while (0)
; #define PG8_LDA(dst, b, h) do { _Pragma("unroll") for (int m = 0; m < 4; ++m) _Pragma("unroll") for (int k = 0; k < 2; ++k) dst[m][k] = *(const PG8_LAS bf16x8*)(lds + PG8_SA(b, h) + aoff + m * 2048 + k * 1024); } while (0)
; #define PG8_LDB(dst, b, h) do { _Pragma("unroll") for (int n = 0; n < 2; ++n) _Pragma("unroll") for (int k = 0; k < 2; ++k) dst[n][k] = *(const PG8_LAS bf16x8*)(lds + PG8_SB(b, h) + boff + n * 2048 + k * 1024); } while (0)
; #define PG8_MMA(ai, bj, At, Bt) do { __builtin_amdgcn_s_setprio(1); _Pragma("unroll") for (int m = 0; m < 4; ++m) _Pragma("unroll") for (int n = 0; n < 2; ++n) _Pragma("unroll") for (int k = 0; k < 2; ++k) \
;         acc[ai][bj][m][n] = __builtin_amdgcn_mfma_f32_16x16x32_bf16(Bt[n][k], At[m][k], acc[ai][bj][m][n], 0, 0, 0); __builtin_amdgcn_s_setprio(0); } while (0)
; #define PG8_WAIT_V(n) asm volatile("s_waitcnt vmcnt(" #n ")" ::: "memory")
; #define PG8_WAIT_L(n) asm volatile("s_waitcnt lgkmcnt(" #n ")" ::: "memory")
; #define PG8_BAR __builtin_amdgcn_s_barrier()
; #define PG8_SCHED __builtin_amdgcn_sched_barrier(0)
; template <class Epi, class Sched, bool ALIGN_EPI = false, bool SP2 = false>
; __device__ __forceinline__ void gemm_phase(PG8_LAS unsigned char* lds, const Gemm g, const Sched& S, const Epi& E) {
;     ...
;         for (int t = 0; t < nt; t += 2) {
;             const bool last = (t == nt - 2);
;             const char* a1 = cA + (size_t)(t + 1) * kstep;
;             const char* a2 = last ? nA : cA + (size_t)(t + 2) * kstep; const char* b2 = last ? nB : cB + (size_t)(t + 2) * kstep;
;             const char* a3 = a2 + kstep; const char* b3 = b2 + kstep;
;             if (last && has_next) S.a_ready(nxt);
;             if constexpr (SP2) {
;             PG8_LDB(B0, 0, 0); PG8_LDB(B1, 0, 1); PG8_SCHED; PG8_LDA(At, 0, 0); PG8_STAGE(PG8_SA(1, 1), a1 + hstep, voffA);
;             PG8_WAIT_V(8); PG8_WAIT_L(0); PG8_BAR; PG8_MMA(0, 0, At, B0); PG8_MMA(0, 1, At, B1); PG8_BAR; PG8_SCHED;
;             PG8_LDA(At, 0, 1); PG8_STAGE(PG8_SB(0, 0), b2, voffB); PG8_STAGE(PG8_SB(0, 1), b2 + hstep, voffB); PG8_STAGE(PG8_SA(0, 0), a2, voffA);
.LBB0_117:
	s_add_u32 s50, s48, 0xfff80080
	s_addc_u32 s51, s49, -1
	s_add_i32 s61, 0, 0x10000
	s_cmp_eq_u32 s58, 28
	s_cselect_b32 s77, s1, s51
	s_cselect_b32 s76, s24, s50
	v_add_u32_e32 v0, s61, v234
	s_cselect_b32 s51, s25, s47
	s_cselect_b32 s50, s38, s39
	s_add_i32 s63, 0, 0x14000
	ds_read_b128 v[124:127], v0
	ds_read_b128 v[128:131], v0 offset:1024
	ds_read_b128 v[132:135], v0 offset:2048
	ds_read_b128 v[140:143], v0 offset:3072
	v_add_u32_e32 v0, s63, v234
	ds_read_b128 v[148:151], v0
	ds_read_b128 v[152:155], v0 offset:1024
	ds_read_b128 v[156:159], v0 offset:2048
	ds_read_b128 v[160:163], v0 offset:3072
	v_lshl_add_u64 v[2:3], s[48:49], 0, v[192:193]
	s_add_i32 m0, s82, 0xc000
	ds_read_b128 v[164:167], v235
	ds_read_b128 v[198:201], v235 offset:1024
	ds_read_b128 v[202:205], v235 offset:2048
	ds_read_b128 v[206:209], v235 offset:3072
	ds_read_b128 v[210:213], v235 offset:4096
	ds_read_b128 v[214:217], v235 offset:5120
	ds_read_b128 v[218:221], v235 offset:6144
	ds_read_b128 v[236:239], v235 offset:7168
	global_load_lds_dwordx4 v[2:3], off
	v_lshl_add_u64 v[2:3], s[48:49], 0, v[194:195]
	s_add_i32 m0, s82, 0xe000
	s_nop 0
	global_load_lds_dwordx4 v[2:3], off
	s_waitcnt vmcnt(8) lgkmcnt(0)
	s_setprio 1
	s_barrier
	v_mfma_f32_16x16x32_bf16 v[144:147], v[124:127], v[164:167], v[144:147]
	v_mfma_f32_16x16x32_bf16 v[136:139], v[132:135], v[164:167], v[136:139]
	v_mfma_f32_16x16x32_bf16 v[112:115], v[124:127], v[202:205], v[112:115]
	v_mfma_f32_16x16x32_bf16 v[108:111], v[132:135], v[202:205], v[108:111]
	v_mfma_f32_16x16x32_bf16 v[96:99], v[124:127], v[210:213], v[96:99]
	v_mfma_f32_16x16x32_bf16 v[92:95], v[132:135], v[210:213], v[92:95]
	v_mfma_f32_16x16x32_bf16 v[80:83], v[124:127], v[218:221], v[80:83]
	v_mfma_f32_16x16x32_bf16 v[76:79], v[132:135], v[218:221], v[76:79]
	v_mfma_f32_16x16x32_bf16 v[144:147], v[128:131], v[198:201], v[144:147]
	v_mfma_f32_16x16x32_bf16 v[136:139], v[140:143], v[198:201], v[136:139]
	v_mfma_f32_16x16x32_bf16 v[112:115], v[128:131], v[206:209], v[112:115]
	v_mfma_f32_16x16x32_bf16 v[108:111], v[140:143], v[206:209], v[108:111]
	v_mfma_f32_16x16x32_bf16 v[96:99], v[128:131], v[214:217], v[96:99]
	v_mfma_f32_16x16x32_bf16 v[92:95], v[140:143], v[214:217], v[92:95]
	v_mfma_f32_16x16x32_bf16 v[80:83], v[128:131], v[236:239], v[80:83]
	v_mfma_f32_16x16x32_bf16 v[76:79], v[140:143], v[236:239], v[76:79]
	s_setprio 0
	s_setprio 1
	v_mfma_f32_16x16x32_bf16 v[120:123], v[148:151], v[164:167], v[120:123]
	v_mfma_f32_16x16x32_bf16 v[116:119], v[156:159], v[164:167], v[116:119]
	v_mfma_f32_16x16x32_bf16 v[104:107], v[148:151], v[202:205], v[104:107]
	v_mfma_f32_16x16x32_bf16 v[100:103], v[156:159], v[202:205], v[100:103]
	v_mfma_f32_16x16x32_bf16 v[88:91], v[148:151], v[210:213], v[88:91]
	v_mfma_f32_16x16x32_bf16 v[84:87], v[156:159], v[210:213], v[84:87]
	v_mfma_f32_16x16x32_bf16 v[72:75], v[148:151], v[218:221], v[72:75]
	v_mfma_f32_16x16x32_bf16 v[68:71], v[156:159], v[218:221], v[68:71]
	v_mfma_f32_16x16x32_bf16 v[120:123], v[152:155], v[198:201], v[120:123]
	v_mfma_f32_16x16x32_bf16 v[116:119], v[160:163], v[198:201], v[116:119]
	v_mfma_f32_16x16x32_bf16 v[104:107], v[152:155], v[206:209], v[104:107]
	v_mfma_f32_16x16x32_bf16 v[100:103], v[160:163], v[206:209], v[100:103]
	v_mfma_f32_16x16x32_bf16 v[88:91], v[152:155], v[214:217], v[88:91]
	v_mfma_f32_16x16x32_bf16 v[84:87], v[160:163], v[214:217], v[84:87]
	v_mfma_f32_16x16x32_bf16 v[72:75], v[152:155], v[236:239], v[72:75]
	v_mfma_f32_16x16x32_bf16 v[68:71], v[160:163], v[236:239], v[68:71]
	s_setprio 0
	s_barrier
	s_add_i32 s61, s61, s73
	v_lshl_add_u64 v[168:169], s[50:51], 0, v[182:183]
	s_mov_b32 m0, s61
	ds_read_b128 v[164:167], v235 offset:16384
	ds_read_b128 v[198:201], v235 offset:17408
	ds_read_b128 v[202:205], v235 offset:18432
	ds_read_b128 v[206:209], v235 offset:19456
	ds_read_b128 v[210:213], v235 offset:20480
	ds_read_b128 v[214:217], v235 offset:21504
	ds_read_b128 v[218:221], v235 offset:22528
	ds_read_b128 v[236:239], v235 offset:23552
	global_load_lds_dwordx4 v[168:169], off
	s_add_i32 m0, s61, 0x2000
	s_add_u32 s78, s50, 0x80000
	v_lshl_add_u64 v[222:223], s[50:51], 0, v[186:187]
	s_addc_u32 s79, s51, 0
	s_add_i32 s61, s63, s73
	global_load_lds_dwordx4 v[222:223], off
	v_lshl_add_u64 v[2:3], s[78:79], 0, v[182:183]
	s_mov_b32 m0, s61
	v_lshl_add_u64 v[244:245], s[76:77], 0, v[180:181]
	global_load_lds_dwordx4 v[2:3], off
	v_lshl_add_u64 v[2:3], s[78:79], 0, v[186:187]
	s_add_i32 m0, s61, 0x2000
	v_lshl_add_u64 v[246:247], s[76:77], 0, v[184:185]
	global_load_lds_dwordx4 v[2:3], off
	s_mov_b32 m0, s82
	s_nop 0
	global_load_lds_dwordx4 v[244:245], off
	s_mov_b32 m0, s83
	s_nop 0
	global_load_lds_dwordx4 v[246:247], off
	s_waitcnt vmcnt(8) lgkmcnt(0)
	s_setprio 1
	s_barrier
; #define PG8_STAGE(bufoff, gbase, voff) do { _Pragma("unroll") for (int _i = 0; _i < 2; ++_i) \
;         __builtin_amdgcn_global_load_lds((const unsigned*)((const char*)(gbase) + (voff)[_i]), (PG8_LAS unsigned*)(lds + (bufoff) + ldsw + _i * 8192), 16, 0, 0); } while (0)
; #define PG8_LDA(dst, b, h) do { _Pragma("unroll") for (int m = 0; m < 4; ++m) _Pragma("unroll") for (int k = 0; k < 2; ++k) dst[m][k] = *(const PG8_LAS bf16x8*)(lds + PG8_SA(b, h) + aoff + m * 2048 + k * 1024); } while (0)
; #define PG8_LDB(dst, b, h) do { _Pragma("unroll") for (int n = 0; n < 2; ++n) _Pragma("unroll") for (int k = 0; k < 2; ++k) dst[n][k] = *(const PG8_LAS bf16x8*)(lds + PG8_SB(b, h) + boff + n * 2048 + k * 1024); } while (0)
; #define PG8_MMA(ai, bj, At, Bt) do { __builtin_amdgcn_s_setprio(1); _Pragma("unroll") for (int m = 0; m < 4; ++m) _Pragma("unroll") for (int n = 0; n < 2; ++n) _Pragma("unroll") for (int k = 0; k < 2; ++k) \
;         acc[ai][bj][m][n] = __builtin_amdgcn_mfma_f32_16x16x32_bf16(Bt[n][k], At[m][k], acc[ai][bj][m][n], 0, 0, 0); __builtin_amdgcn_s_setprio(0); } while (0)
; #define PG8_WAIT_V(n) asm volatile("s_waitcnt vmcnt(" #n ")" ::: "memory")
; #define PG8_WAIT_L(n) asm volatile("s_waitcnt lgkmcnt(" #n ")" ::: "memory")
; #define PG8_BAR __builtin_amdgcn_s_barrier()
; #define PG8_SCHED __builtin_amdgcn_sched_barrier(0)
; template <class Epi, class Sched, bool ALIGN_EPI = false, bool SP2 = false>
; __device__ __forceinline__ void gemm_phase(PG8_LAS unsigned char* lds, const Gemm g, const Sched& S, const Epi& E) {
;     ...
;             PG8_WAIT_V(8); PG8_WAIT_L(0); PG8_BAR; PG8_MMA(1, 0, At, B0); PG8_MMA(1, 1, At, B1); PG8_BAR; PG8_SCHED;
;             PG8_LDB(B0, 1, 0); PG8_LDB(B1, 1, 1); PG8_SCHED; PG8_LDA(At, 1, 0); PG8_STAGE(PG8_SA(0, 1), a2 + hstep, voffA);
;             PG8_WAIT_V(8); PG8_WAIT_L(0); PG8_BAR; PG8_MMA(0, 0, At, B0); PG8_MMA(0, 1, At, B1); PG8_BAR; PG8_SCHED;
	v_mfma_f32_16x16x32_bf16 v[64:67], v[124:127], v[164:167], v[64:67]
	v_mfma_f32_16x16x32_bf16 v[60:63], v[132:135], v[164:167], v[60:63]
	v_mfma_f32_16x16x32_bf16 v[48:51], v[124:127], v[202:205], v[48:51]
	v_mfma_f32_16x16x32_bf16 v[44:47], v[132:135], v[202:205], v[44:47]
	v_mfma_f32_16x16x32_bf16 v[32:35], v[124:127], v[210:213], v[32:35]
	v_mfma_f32_16x16x32_bf16 v[28:31], v[132:135], v[210:213], v[28:31]
	v_mfma_f32_16x16x32_bf16 v[16:19], v[124:127], v[218:221], v[16:19]
	v_mfma_f32_16x16x32_bf16 v[12:15], v[132:135], v[218:221], v[12:15]
	v_mfma_f32_16x16x32_bf16 v[64:67], v[128:131], v[198:201], v[64:67]
	v_mfma_f32_16x16x32_bf16 v[60:63], v[140:143], v[198:201], v[60:63]
	v_mfma_f32_16x16x32_bf16 v[48:51], v[128:131], v[206:209], v[48:51]
	v_mfma_f32_16x16x32_bf16 v[44:47], v[140:143], v[206:209], v[44:47]
	v_mfma_f32_16x16x32_bf16 v[32:35], v[128:131], v[214:217], v[32:35]
	v_mfma_f32_16x16x32_bf16 v[28:31], v[140:143], v[214:217], v[28:31]
	v_mfma_f32_16x16x32_bf16 v[16:19], v[128:131], v[236:239], v[16:19]
	v_mfma_f32_16x16x32_bf16 v[12:15], v[140:143], v[236:239], v[12:15]
	s_setprio 0
	s_setprio 1
	v_mfma_f32_16x16x32_bf16 v[56:59], v[148:151], v[164:167], v[56:59]
	v_mfma_f32_16x16x32_bf16 v[52:55], v[156:159], v[164:167], v[52:55]
	v_mfma_f32_16x16x32_bf16 v[40:43], v[148:151], v[202:205], v[40:43]
	v_mfma_f32_16x16x32_bf16 v[36:39], v[156:159], v[202:205], v[36:39]
	v_mfma_f32_16x16x32_bf16 v[24:27], v[148:151], v[210:213], v[24:27]
	v_mfma_f32_16x16x32_bf16 v[20:23], v[156:159], v[210:213], v[20:23]
	v_mfma_f32_16x16x32_bf16 v[8:11], v[148:151], v[218:221], v[8:11]
	v_mfma_f32_16x16x32_bf16 v[2:5], v[156:159], v[218:221], v[4:7]
	v_mfma_f32_16x16x32_bf16 v[56:59], v[152:155], v[198:201], v[56:59]
	v_mfma_f32_16x16x32_bf16 v[52:55], v[160:163], v[198:201], v[52:55]
	v_mfma_f32_16x16x32_bf16 v[40:43], v[152:155], v[206:209], v[40:43]
	v_mfma_f32_16x16x32_bf16 v[36:39], v[160:163], v[206:209], v[36:39]
	v_mfma_f32_16x16x32_bf16 v[24:27], v[152:155], v[214:217], v[24:27]
	v_mfma_f32_16x16x32_bf16 v[20:23], v[160:163], v[214:217], v[20:23]
	v_mfma_f32_16x16x32_bf16 v[8:11], v[152:155], v[236:239], v[8:11]
	v_mfma_f32_16x16x32_bf16 v[2:5], v[160:163], v[236:239], v[2:5]
	s_setprio 0
	s_barrier
	s_add_i32 s61, 0, 0x18000
	v_add_u32_e32 v0, s61, v234
	s_add_i32 s63, 0, 0x1c000
	ds_read_b128 v[124:127], v0
	ds_read_b128 v[128:131], v0 offset:1024
	ds_read_b128 v[132:135], v0 offset:2048
	ds_read_b128 v[140:143], v0 offset:3072
	v_add_u32_e32 v0, s63, v234
	ds_read_b128 v[148:151], v0
	ds_read_b128 v[152:155], v0 offset:1024
	ds_read_b128 v[156:159], v0 offset:2048
	ds_read_b128 v[160:163], v0 offset:3072
	s_add_u32 s76, s76, 0x80000
	s_addc_u32 s77, s77, 0
	s_mov_b32 m0, s84
	v_lshl_add_u64 v[6:7], s[76:77], 0, v[180:181]
	ds_read_b128 v[164:167], v235 offset:32768
	ds_read_b128 v[198:201], v235 offset:33792
	ds_read_b128 v[202:205], v235 offset:34816
	ds_read_b128 v[206:209], v235 offset:35840
	ds_read_b128 v[210:213], v235 offset:36864
	ds_read_b128 v[214:217], v235 offset:37888
	ds_read_b128 v[218:221], v235 offset:38912
	ds_read_b128 v[236:239], v235 offset:39936
	global_load_lds_dwordx4 v[6:7], off
	v_lshl_add_u64 v[6:7], s[76:77], 0, v[184:185]
	s_mov_b32 m0, s85
	s_nop 0
	global_load_lds_dwordx4 v[6:7], off
	s_waitcnt vmcnt(8) lgkmcnt(0)
	s_setprio 1
	s_barrier
	v_mfma_f32_16x16x32_bf16 v[144:147], v[124:127], v[164:167], v[144:147]
	v_mfma_f32_16x16x32_bf16 v[136:139], v[132:135], v[164:167], v[136:139]
	v_mfma_f32_16x16x32_bf16 v[112:115], v[124:127], v[202:205], v[112:115]
	v_mfma_f32_16x16x32_bf16 v[108:111], v[132:135], v[202:205], v[108:111]
	v_mfma_f32_16x16x32_bf16 v[96:99], v[124:127], v[210:213], v[96:99]
	v_mfma_f32_16x16x32_bf16 v[92:95], v[132:135], v[210:213], v[92:95]
	v_mfma_f32_16x16x32_bf16 v[80:83], v[124:127], v[218:221], v[80:83]
	v_mfma_f32_16x16x32_bf16 v[76:79], v[132:135], v[218:221], v[76:79]
	v_mfma_f32_16x16x32_bf16 v[144:147], v[128:131], v[198:201], v[144:147]
	v_mfma_f32_16x16x32_bf16 v[136:139], v[140:143], v[198:201], v[136:139]
	v_mfma_f32_16x16x32_bf16 v[112:115], v[128:131], v[206:209], v[112:115]
	v_mfma_f32_16x16x32_bf16 v[108:111], v[140:143], v[206:209], v[108:111]
	v_mfma_f32_16x16x32_bf16 v[96:99], v[128:131], v[214:217], v[96:99]
	v_mfma_f32_16x16x32_bf16 v[92:95], v[140:143], v[214:217], v[92:95]
	v_mfma_f32_16x16x32_bf16 v[80:83], v[128:131], v[236:239], v[80:83]
	v_mfma_f32_16x16x32_bf16 v[76:79], v[140:143], v[236:239], v[76:79]
	s_setprio 0
	s_setprio 1
	v_mfma_f32_16x16x32_bf16 v[120:123], v[148:151], v[164:167], v[120:123]
	v_mfma_f32_16x16x32_bf16 v[116:119], v[156:159], v[164:167], v[116:119]
	v_mfma_f32_16x16x32_bf16 v[104:107], v[148:151], v[202:205], v[104:107]
	v_mfma_f32_16x16x32_bf16 v[100:103], v[156:159], v[202:205], v[100:103]
	v_mfma_f32_16x16x32_bf16 v[88:91], v[148:151], v[210:213], v[88:91]
	v_mfma_f32_16x16x32_bf16 v[84:87], v[156:159], v[210:213], v[84:87]
	v_mfma_f32_16x16x32_bf16 v[72:75], v[148:151], v[218:221], v[72:75]
	v_mfma_f32_16x16x32_bf16 v[68:71], v[156:159], v[218:221], v[68:71]
	v_mfma_f32_16x16x32_bf16 v[120:123], v[152:155], v[198:201], v[120:123]
	v_mfma_f32_16x16x32_bf16 v[116:119], v[160:163], v[198:201], v[116:119]
	v_mfma_f32_16x16x32_bf16 v[104:107], v[152:155], v[206:209], v[104:107]
	v_mfma_f32_16x16x32_bf16 v[100:103], v[160:163], v[206:209], v[100:103]
	v_mfma_f32_16x16x32_bf16 v[88:91], v[152:155], v[214:217], v[88:91]
	v_mfma_f32_16x16x32_bf16 v[84:87], v[160:163], v[214:217], v[84:87]
	v_mfma_f32_16x16x32_bf16 v[72:75], v[152:155], v[236:239], v[72:75]
	v_mfma_f32_16x16x32_bf16 v[68:71], v[160:163], v[236:239], v[68:71]
	s_setprio 0
	s_barrier
; #define PG8_STAGE(bufoff, gbase, voff) do { _Pragma("unroll") for (int _i = 0; _i < 2; ++_i) \
;         __builtin_amdgcn_global_load_lds((const unsigned*)((const char*)(gbase) + (voff)[_i]), (PG8_LAS unsigned*)(lds + (bufoff) + ldsw + _i * 8192), 16, 0, 0); } while (0)
; #define PG8_LDA(dst, b, h) do { _Pragma("unroll") for (int m = 0; m < 4; ++m) _Pragma("unroll") for (int k = 0; k < 2; ++k) dst[m][k] = *(const PG8_LAS bf16x8*)(lds + PG8_SA(b, h) + aoff + m * 2048 + k * 1024); } while (0)
; #define PG8_MMA(ai, bj, At, Bt) do { __builtin_amdgcn_s_setprio(1); _Pragma("unroll") for (int m = 0; m < 4; ++m) _Pragma("unroll") for (int n = 0; n < 2; ++n) _Pragma("unroll") for (int k = 0; k < 2; ++k) \
;         acc[ai][bj][m][n] = __builtin_amdgcn_mfma_f32_16x16x32_bf16(Bt[n][k], At[m][k], acc[ai][bj][m][n], 0, 0, 0); __builtin_amdgcn_s_setprio(0); } while (0)
; #define PG8_WAIT_V(n) asm volatile("s_waitcnt vmcnt(" #n ")" ::: "memory")
; #define PG8_WAIT_L(n) asm volatile("s_waitcnt lgkmcnt(" #n ")" ::: "memory")
; #define PG8_BAR __builtin_amdgcn_s_barrier()
; #define PG8_SCHED __builtin_amdgcn_sched_barrier(0)
; template <class Epi, class Sched, bool ALIGN_EPI = false, bool SP2 = false>
; __device__ __forceinline__ void gemm_phase(PG8_LAS unsigned char* lds, const Gemm g, const Sched& S, const Epi& E) {
;     ...
;             PG8_LDA(At, 1, 1); PG8_STAGE(PG8_SB(1, 0), b3, voffB); PG8_STAGE(PG8_SB(1, 1), b3 + hstep, voffB); PG8_STAGE(PG8_SA(1, 0), a3, voffA);
;             PG8_WAIT_V(8); PG8_WAIT_L(0); PG8_BAR; PG8_MMA(1, 0, At, B0); PG8_MMA(1, 1, At, B1); PG8_BAR; PG8_SCHED;
;     ...
;         }
;         if constexpr (ALIGN_EPI) { if (wr == 0) PG8_BAR; }
	s_add_i32 s61, s61, s73
	v_lshl_add_u64 v[6:7], v[168:169], 0, s[12:13]
	s_mov_b32 m0, s61
	ds_read_b128 v[164:167], v235 offset:49152
	ds_read_b128 v[198:201], v235 offset:50176
	ds_read_b128 v[202:205], v235 offset:51200
	ds_read_b128 v[206:209], v235 offset:52224
	ds_read_b128 v[210:213], v235 offset:53248
	ds_read_b128 v[214:217], v235 offset:54272
	ds_read_b128 v[218:221], v235 offset:55296
	ds_read_b128 v[236:239], v235 offset:56320
	global_load_lds_dwordx4 v[6:7], off
	s_add_i32 m0, s61, 0x2000
	s_add_u32 s50, s50, 0x80080
	v_lshl_add_u64 v[6:7], v[222:223], 0, s[12:13]
	s_addc_u32 s51, s51, 0
	s_add_i32 s61, s63, s73
	global_load_lds_dwordx4 v[6:7], off
	v_lshl_add_u64 v[6:7], s[50:51], 0, v[182:183]
	s_mov_b32 m0, s61
	s_nop 0
	global_load_lds_dwordx4 v[6:7], off
	v_lshl_add_u64 v[6:7], s[50:51], 0, v[186:187]
	s_add_i32 m0, s61, 0x2000
	s_nop 0
	global_load_lds_dwordx4 v[6:7], off
	v_lshl_add_u64 v[6:7], v[244:245], 0, s[12:13]
	s_mov_b32 m0, s87
	s_nop 0
	global_load_lds_dwordx4 v[6:7], off
	v_lshl_add_u64 v[6:7], v[246:247], 0, s[12:13]
	s_mov_b32 m0, s88
	s_nop 0
	global_load_lds_dwordx4 v[6:7], off
	s_waitcnt vmcnt(8) lgkmcnt(0)
	s_setprio 1
	s_barrier
	v_mfma_f32_16x16x32_bf16 v[64:67], v[124:127], v[164:167], v[64:67]
	v_mfma_f32_16x16x32_bf16 v[60:63], v[132:135], v[164:167], v[60:63]
	v_mfma_f32_16x16x32_bf16 v[48:51], v[124:127], v[202:205], v[48:51]
	v_mfma_f32_16x16x32_bf16 v[44:47], v[132:135], v[202:205], v[44:47]
	v_mfma_f32_16x16x32_bf16 v[32:35], v[124:127], v[210:213], v[32:35]
	v_mfma_f32_16x16x32_bf16 v[28:31], v[132:135], v[210:213], v[28:31]
	v_mfma_f32_16x16x32_bf16 v[16:19], v[124:127], v[218:221], v[16:19]
	v_mfma_f32_16x16x32_bf16 v[12:15], v[132:135], v[218:221], v[12:15]
	v_mfma_f32_16x16x32_bf16 v[64:67], v[128:131], v[198:201], v[64:67]
	v_mfma_f32_16x16x32_bf16 v[60:63], v[140:143], v[198:201], v[60:63]
	v_mfma_f32_16x16x32_bf16 v[48:51], v[128:131], v[206:209], v[48:51]
	v_mfma_f32_16x16x32_bf16 v[44:47], v[140:143], v[206:209], v[44:47]
	v_mfma_f32_16x16x32_bf16 v[32:35], v[128:131], v[214:217], v[32:35]
	v_mfma_f32_16x16x32_bf16 v[28:31], v[140:143], v[214:217], v[28:31]
	v_mfma_f32_16x16x32_bf16 v[16:19], v[128:131], v[236:239], v[16:19]
	v_mfma_f32_16x16x32_bf16 v[12:15], v[140:143], v[236:239], v[12:15]
	s_setprio 0
	s_setprio 1
	v_mfma_f32_16x16x32_bf16 v[56:59], v[148:151], v[164:167], v[56:59]
	v_mfma_f32_16x16x32_bf16 v[52:55], v[156:159], v[164:167], v[52:55]
	v_mfma_f32_16x16x32_bf16 v[40:43], v[148:151], v[202:205], v[40:43]
	v_mfma_f32_16x16x32_bf16 v[36:39], v[156:159], v[202:205], v[36:39]
	v_mfma_f32_16x16x32_bf16 v[24:27], v[148:151], v[210:213], v[24:27]
	v_mfma_f32_16x16x32_bf16 v[20:23], v[156:159], v[210:213], v[20:23]
	v_mfma_f32_16x16x32_bf16 v[6:9], v[148:151], v[218:221], v[8:11]
	v_mfma_f32_16x16x32_bf16 v[2:5], v[156:159], v[218:221], v[2:5]
	v_mfma_f32_16x16x32_bf16 v[56:59], v[152:155], v[198:201], v[56:59]
	v_mfma_f32_16x16x32_bf16 v[52:55], v[160:163], v[198:201], v[52:55]
	v_mfma_f32_16x16x32_bf16 v[40:43], v[152:155], v[206:209], v[40:43]
	v_mfma_f32_16x16x32_bf16 v[36:39], v[160:163], v[206:209], v[36:39]
	v_mfma_f32_16x16x32_bf16 v[24:27], v[152:155], v[214:217], v[24:27]
	v_mfma_f32_16x16x32_bf16 v[20:23], v[160:163], v[214:217], v[20:23]
	v_mfma_f32_16x16x32_bf16 v[8:11], v[152:155], v[236:239], v[6:9]
	v_mfma_f32_16x16x32_bf16 v[4:7], v[160:163], v[236:239], v[2:5]
	s_setprio 0
	s_barrier
	s_add_i32 s58, s58, 2
	s_add_u32 s48, s48, 0x100
	s_addc_u32 s49, s49, 0
	s_add_u32 s39, s39, 0x100
	s_addc_u32 s47, s47, 0
	s_cmp_gt_u32 s58, 29
	s_cbranch_scc0 .LBB0_117
	s_and_b64 vcc, exec, s[30:31]
	s_cbranch_vccz .LBB0_120
	s_barrier

; #define PG8_STAGE(bufoff, gbase, voff) do { _Pragma("unroll") for (int _i = 0; _i < 2; ++_i) \
;         __builtin_amdgcn_global_load_lds((const unsigned*)((const char*)(gbase) + (voff)[_i]), (PG8_LAS unsigned*)(lds + (bufoff) + ldsw + _i * 8192), 16, 0, 0); } while (0)
; #define PG8_LDA(dst, b, h) do { _Pragma("unroll") for (int m = 0; m < 4; ++m) _Pragma("unroll") for (int k = 0; k < 2; ++k) dst[m][k] = *(const PG8_LAS bf16x8*)(lds + PG8_SA(b, h) + aoff + m * 2048 + k * 1024); } while (0)
; #define PG8_LDB(dst, b, h) do { _Pragma("unroll") for (int n = 0; n < 2; ++n) _Pragma("unroll") for (int k = 0; k < 2; ++k) dst[n][k] = *(const PG8_LAS bf16x8*)(lds + PG8_SB(b, h) + boff + n * 2048 + k * 1024); } while (0)
; #define PG8_MMA(ai, bj, At, Bt) do { __builtin_amdgcn_s_setprio(1); _Pragma("unroll") for (int m = 0; m < 4; ++m) _Pragma("unroll") for (int n = 0; n < 2; ++n) _Pragma("unroll") for (int k = 0; k < 2; ++k) \
;         acc[ai][bj][m][n] = __builtin_amdgcn_mfma_f32_16x16x32_bf16(Bt[n][k], At[m][k], acc[ai][bj][m][n], 0, 0, 0); __builtin_amdgcn_s_setprio(0); } while (0)
; #define PG8_WAIT_V(n) asm volatile("s_waitcnt vmcnt(" #n ")" ::: "memory")
; #define PG8_WAIT_L(n) asm volatile("s_waitcnt lgkmcnt(" #n ")" ::: "memory")
; #define PG8_BAR __builtin_amdgcn_s_barrier()
; #define PG8_SCHED __builtin_amdgcn_sched_barrier(0)
; template <class Epi, class Sched, bool ALIGN_EPI = false, bool SP2 = false>
; __device__ __forceinline__ void gemm_phase(PG8_LAS unsigned char* lds, const Gemm g, const Sched& S, const Epi& E) {
;     ...
;         for (int t = 0; t < nt; t += 2) {
;             const bool last = (t == nt - 2);
;             const char* a1 = cA + (size_t)(t + 1) * kstep;
;             const char* a2 = last ? nA : cA + (size_t)(t + 2) * kstep; const char* b2 = last ? nB : cB + (size_t)(t + 2) * kstep;
;             const char* a3 = a2 + kstep; const char* b3 = b2 + kstep;
;             if (last && has_next) S.a_ready(nxt);
;             if constexpr (SP2) {
;             PG8_LDB(B0, 0, 0); PG8_LDB(B1, 0, 1); PG8_SCHED; PG8_LDA(At, 0, 0); PG8_STAGE(PG8_SA(1, 1), a1 + hstep, voffA);
;             PG8_WAIT_V(8); PG8_WAIT_L(0); PG8_BAR; PG8_MMA(0, 0, At, B0); PG8_MMA(0, 1, At, B1); PG8_BAR; PG8_SCHED;
;             PG8_LDA(At, 0, 1); PG8_STAGE(PG8_SB(0, 0), b2, voffB); PG8_STAGE(PG8_SB(0, 1), b2 + hstep, voffB); PG8_STAGE(PG8_SA(0, 0), a2, voffA);
.LBB0_1427:
	s_add_i32 s96, s74, 2
	s_add_u32 s97, s44, 0x80
	s_addc_u32 s75, s45, 0
	s_add_i32 s27, 0, 0x10000
	s_cmp_eq_u32 s91, s74
	s_cselect_b32 s75, s24, s75
	s_cselect_b32 s74, s25, s97
	s_cselect_b32 vcc_hi, s53, s95
	s_cselect_b32 vcc_lo, s61, s94
	s_add_i32 s97, 0, 0x14000
	v_add_u32_e32 v142, s27, v185
	v_add_u32_e32 v168, s97, v185
	ds_read_b128 v[130:133], v142
	ds_read_b128 v[134:137], v142 offset:1024
	ds_read_b128 v[138:141], v142 offset:2048
	ds_read_b128 v[142:145], v142 offset:3072
	ds_read_b128 v[146:149], v168
	ds_read_b128 v[150:153], v168 offset:1024
	ds_read_b128 v[164:167], v168 offset:2048
	ds_read_b128 v[180:183], v168 offset:3072
	v_lshl_add_u64 v[168:169], s[44:45], 0, v[160:161]
	s_add_i32 m0, s83, 0xc000
	ds_read_b128 v[190:193], v187
	ds_read_b128 v[194:197], v187 offset:1024
	ds_read_b128 v[198:201], v187 offset:2048
	ds_read_b128 v[202:205], v187 offset:3072
	ds_read_b128 v[206:209], v187 offset:4096
	ds_read_b128 v[210:213], v187 offset:5120
	ds_read_b128 v[214:217], v187 offset:6144
	ds_read_b128 v[218:221], v187 offset:7168
	global_load_lds_dwordx4 v[168:169], off
	v_lshl_add_u64 v[168:169], s[44:45], 0, v[162:163]
	s_add_i32 m0, s83, 0xe000
	s_nop 0
	global_load_lds_dwordx4 v[168:169], off
	s_waitcnt vmcnt(8) lgkmcnt(0)
	s_setprio 1
	s_barrier
	v_mfma_f32_16x16x32_bf16 v[126:129], v[130:133], v[190:193], v[126:129]
	v_mfma_f32_16x16x32_bf16 v[122:125], v[138:141], v[190:193], v[122:125]
	v_mfma_f32_16x16x32_bf16 v[110:113], v[130:133], v[198:201], v[110:113]
	v_mfma_f32_16x16x32_bf16 v[106:109], v[138:141], v[198:201], v[106:109]
	v_mfma_f32_16x16x32_bf16 v[94:97], v[130:133], v[206:209], v[94:97]
	v_mfma_f32_16x16x32_bf16 v[90:93], v[138:141], v[206:209], v[90:93]
	v_mfma_f32_16x16x32_bf16 v[78:81], v[130:133], v[214:217], v[78:81]
	v_mfma_f32_16x16x32_bf16 v[74:77], v[138:141], v[214:217], v[74:77]
	v_mfma_f32_16x16x32_bf16 v[126:129], v[134:137], v[194:197], v[126:129]
	v_mfma_f32_16x16x32_bf16 v[122:125], v[142:145], v[194:197], v[122:125]
	v_mfma_f32_16x16x32_bf16 v[110:113], v[134:137], v[202:205], v[110:113]
	v_mfma_f32_16x16x32_bf16 v[106:109], v[142:145], v[202:205], v[106:109]
	v_mfma_f32_16x16x32_bf16 v[94:97], v[134:137], v[210:213], v[94:97]
	v_mfma_f32_16x16x32_bf16 v[90:93], v[142:145], v[210:213], v[90:93]
	v_mfma_f32_16x16x32_bf16 v[78:81], v[134:137], v[218:221], v[78:81]
	v_mfma_f32_16x16x32_bf16 v[74:77], v[142:145], v[218:221], v[74:77]
	s_setprio 0
	s_setprio 1
	v_mfma_f32_16x16x32_bf16 v[118:121], v[146:149], v[190:193], v[118:121]
	v_mfma_f32_16x16x32_bf16 v[114:117], v[164:167], v[190:193], v[114:117]
	v_mfma_f32_16x16x32_bf16 v[102:105], v[146:149], v[198:201], v[102:105]
	v_mfma_f32_16x16x32_bf16 v[98:101], v[164:167], v[198:201], v[98:101]
	v_mfma_f32_16x16x32_bf16 v[86:89], v[146:149], v[206:209], v[86:89]
	v_mfma_f32_16x16x32_bf16 v[82:85], v[164:167], v[206:209], v[82:85]
	v_mfma_f32_16x16x32_bf16 v[70:73], v[146:149], v[214:217], v[70:73]
	v_mfma_f32_16x16x32_bf16 v[66:69], v[164:167], v[214:217], v[66:69]
	v_mfma_f32_16x16x32_bf16 v[118:121], v[150:153], v[194:197], v[118:121]
	v_mfma_f32_16x16x32_bf16 v[114:117], v[180:183], v[194:197], v[114:117]
	v_mfma_f32_16x16x32_bf16 v[102:105], v[150:153], v[202:205], v[102:105]
	v_mfma_f32_16x16x32_bf16 v[98:101], v[180:183], v[202:205], v[98:101]
	v_mfma_f32_16x16x32_bf16 v[86:89], v[150:153], v[210:213], v[86:89]
	v_mfma_f32_16x16x32_bf16 v[82:85], v[180:183], v[210:213], v[82:85]
	v_mfma_f32_16x16x32_bf16 v[70:73], v[150:153], v[218:221], v[70:73]
	v_mfma_f32_16x16x32_bf16 v[66:69], v[180:183], v[218:221], v[66:69]
	s_setprio 0
	s_barrier
	s_add_i32 s27, s27, s82
	v_lshl_add_u64 v[168:169], vcc, 0, v[0:1]
	s_mov_b32 m0, s27
	ds_read_b128 v[190:193], v187 offset:16384
	ds_read_b128 v[194:197], v187 offset:17408
	ds_read_b128 v[198:201], v187 offset:18432
	ds_read_b128 v[202:205], v187 offset:19456
	ds_read_b128 v[206:209], v187 offset:20480
	ds_read_b128 v[210:213], v187 offset:21504
	ds_read_b128 v[214:217], v187 offset:22528
	ds_read_b128 v[218:221], v187 offset:23552
	global_load_lds_dwordx4 v[168:169], off
	s_add_i32 m0, s27, 0x2000
	v_lshl_add_u64 v[222:223], vcc, 0, v[154:155]
	s_add_u32 vcc_lo, vcc_lo, s70
	s_addc_u32 vcc_hi, vcc_hi, 0
	s_add_i32 s27, s97, s82
	global_load_lds_dwordx4 v[222:223], off
	v_lshl_add_u64 v[232:233], vcc, 0, v[0:1]
	s_mov_b32 m0, s27
	v_lshl_add_u64 v[234:235], vcc, 0, v[154:155]
	global_load_lds_dwordx4 v[232:233], off
	s_add_i32 m0, s27, 0x2000
	v_lshl_add_u64 v[236:237], s[74:75], 0, v[158:159]
	global_load_lds_dwordx4 v[234:235], off
	s_mov_b32 m0, s83
	v_lshl_add_u64 v[238:239], s[74:75], 0, v[156:157]
	global_load_lds_dwordx4 v[236:237], off
	s_mov_b32 m0, s84
	s_nop 0
	global_load_lds_dwordx4 v[238:239], off
	s_waitcnt vmcnt(8) lgkmcnt(0)
	s_setprio 1
	s_barrier
; #define PG8_STAGE(bufoff, gbase, voff) do { _Pragma("unroll") for (int _i = 0; _i < 2; ++_i) \
;         __builtin_amdgcn_global_load_lds((const unsigned*)((const char*)(gbase) + (voff)[_i]), (PG8_LAS unsigned*)(lds + (bufoff) + ldsw + _i * 8192), 16, 0, 0); } while (0)
; #define PG8_LDA(dst, b, h) do { _Pragma("unroll") for (int m = 0; m < 4; ++m) _Pragma("unroll") for (int k = 0; k < 2; ++k) dst[m][k] = *(const PG8_LAS bf16x8*)(lds + PG8_SA(b, h) + aoff + m * 2048 + k * 1024); } while (0)
; #define PG8_LDB(dst, b, h) do { _Pragma("unroll") for (int n = 0; n < 2; ++n) _Pragma("unroll") for (int k = 0; k < 2; ++k) dst[n][k] = *(const PG8_LAS bf16x8*)(lds + PG8_SB(b, h) + boff + n * 2048 + k * 1024); } while (0)
; #define PG8_MMA(ai, bj, At, Bt) do { __builtin_amdgcn_s_setprio(1); _Pragma("unroll") for (int m = 0; m < 4; ++m) _Pragma("unroll") for (int n = 0; n < 2; ++n) _Pragma("unroll") for (int k = 0; k < 2; ++k) \
;         acc[ai][bj][m][n] = __builtin_amdgcn_mfma_f32_16x16x32_bf16(Bt[n][k], At[m][k], acc[ai][bj][m][n], 0, 0, 0); __builtin_amdgcn_s_setprio(0); } while (0)
; #define PG8_WAIT_V(n) asm volatile("s_waitcnt vmcnt(" #n ")" ::: "memory")
; #define PG8_WAIT_L(n) asm volatile("s_waitcnt lgkmcnt(" #n ")" ::: "memory")
; #define PG8_BAR __builtin_amdgcn_s_barrier()
; #define PG8_SCHED __builtin_amdgcn_sched_barrier(0)
; template <class Epi, class Sched, bool ALIGN_EPI = false, bool SP2 = false>
; __device__ __forceinline__ void gemm_phase(PG8_LAS unsigned char* lds, const Gemm g, const Sched& S, const Epi& E) {
;     ...
;             PG8_WAIT_V(8); PG8_WAIT_L(0); PG8_BAR; PG8_MMA(1, 0, At, B0); PG8_MMA(1, 1, At, B1); PG8_BAR; PG8_SCHED;
;             PG8_LDB(B0, 1, 0); PG8_LDB(B1, 1, 1); PG8_SCHED; PG8_LDA(At, 1, 0); PG8_STAGE(PG8_SA(0, 1), a2 + hstep, voffA);
;             PG8_WAIT_V(8); PG8_WAIT_L(0); PG8_BAR; PG8_MMA(0, 0, At, B0); PG8_MMA(0, 1, At, B1); PG8_BAR; PG8_SCHED;
	v_mfma_f32_16x16x32_bf16 v[62:65], v[130:133], v[190:193], v[62:65]
	v_mfma_f32_16x16x32_bf16 v[58:61], v[138:141], v[190:193], v[58:61]
	v_mfma_f32_16x16x32_bf16 v[46:49], v[130:133], v[198:201], v[46:49]
	v_mfma_f32_16x16x32_bf16 v[42:45], v[138:141], v[198:201], v[42:45]
	v_mfma_f32_16x16x32_bf16 v[30:33], v[130:133], v[206:209], v[30:33]
	v_mfma_f32_16x16x32_bf16 v[26:29], v[138:141], v[206:209], v[26:29]
	v_mfma_f32_16x16x32_bf16 v[14:17], v[130:133], v[214:217], v[14:17]
	v_mfma_f32_16x16x32_bf16 v[10:13], v[138:141], v[214:217], v[10:13]
	v_mfma_f32_16x16x32_bf16 v[62:65], v[134:137], v[194:197], v[62:65]
	v_mfma_f32_16x16x32_bf16 v[58:61], v[142:145], v[194:197], v[58:61]
	v_mfma_f32_16x16x32_bf16 v[46:49], v[134:137], v[202:205], v[46:49]
	v_mfma_f32_16x16x32_bf16 v[42:45], v[142:145], v[202:205], v[42:45]
	v_mfma_f32_16x16x32_bf16 v[30:33], v[134:137], v[210:213], v[30:33]
	v_mfma_f32_16x16x32_bf16 v[26:29], v[142:145], v[210:213], v[26:29]
	v_mfma_f32_16x16x32_bf16 v[14:17], v[134:137], v[218:221], v[14:17]
	v_mfma_f32_16x16x32_bf16 v[10:13], v[142:145], v[218:221], v[10:13]
	s_setprio 0
	s_setprio 1
	v_mfma_f32_16x16x32_bf16 v[54:57], v[146:149], v[190:193], v[54:57]
	v_mfma_f32_16x16x32_bf16 v[50:53], v[164:167], v[190:193], v[50:53]
	v_mfma_f32_16x16x32_bf16 v[38:41], v[146:149], v[198:201], v[38:41]
	v_mfma_f32_16x16x32_bf16 v[34:37], v[164:167], v[198:201], v[34:37]
	v_mfma_f32_16x16x32_bf16 v[22:25], v[146:149], v[206:209], v[22:25]
	v_mfma_f32_16x16x32_bf16 v[18:21], v[164:167], v[206:209], v[18:21]
	v_mfma_f32_16x16x32_bf16 v[6:9], v[146:149], v[214:217], v[6:9]
	v_mfma_f32_16x16x32_bf16 v[2:5], v[164:167], v[214:217], v[2:5]
	v_mfma_f32_16x16x32_bf16 v[54:57], v[150:153], v[194:197], v[54:57]
	v_mfma_f32_16x16x32_bf16 v[50:53], v[180:183], v[194:197], v[50:53]
	v_mfma_f32_16x16x32_bf16 v[38:41], v[150:153], v[202:205], v[38:41]
	v_mfma_f32_16x16x32_bf16 v[34:37], v[180:183], v[202:205], v[34:37]
	v_mfma_f32_16x16x32_bf16 v[22:25], v[150:153], v[210:213], v[22:25]
	v_mfma_f32_16x16x32_bf16 v[18:21], v[180:183], v[210:213], v[18:21]
	v_mfma_f32_16x16x32_bf16 v[6:9], v[150:153], v[218:221], v[6:9]
	v_mfma_f32_16x16x32_bf16 v[2:5], v[180:183], v[218:221], v[2:5]
	s_setprio 0
	s_barrier
	s_add_i32 s27, 0, 0x18000
	s_add_i32 s97, 0, 0x1c000
	v_add_u32_e32 v142, s27, v185
	v_add_u32_e32 v180, s97, v185
	ds_read_b128 v[130:133], v142
	ds_read_b128 v[134:137], v142 offset:1024
	ds_read_b128 v[138:141], v142 offset:2048
	ds_read_b128 v[142:145], v142 offset:3072
	ds_read_b128 v[146:149], v180
	ds_read_b128 v[150:153], v180 offset:1024
	ds_read_b128 v[164:167], v180 offset:2048
	ds_read_b128 v[180:183], v180 offset:3072
	s_add_u32 s74, s74, s70
	s_addc_u32 s75, s75, 0
	s_mov_b32 m0, s85
	v_lshl_add_u64 v[244:245], s[74:75], 0, v[158:159]
	ds_read_b128 v[190:193], v187 offset:32768
	ds_read_b128 v[194:197], v187 offset:33792
	ds_read_b128 v[198:201], v187 offset:34816
	ds_read_b128 v[202:205], v187 offset:35840
	ds_read_b128 v[206:209], v187 offset:36864
	ds_read_b128 v[210:213], v187 offset:37888
	ds_read_b128 v[214:217], v187 offset:38912
	ds_read_b128 v[218:221], v187 offset:39936
	global_load_lds_dwordx4 v[244:245], off
	v_lshl_add_u64 v[244:245], s[74:75], 0, v[156:157]
	s_mov_b32 m0, s86
	s_nop 0
	global_load_lds_dwordx4 v[244:245], off
	s_waitcnt vmcnt(8) lgkmcnt(0)
	s_setprio 1
	s_barrier
	v_mfma_f32_16x16x32_bf16 v[126:129], v[130:133], v[190:193], v[126:129]
	v_mfma_f32_16x16x32_bf16 v[122:125], v[138:141], v[190:193], v[122:125]
	v_mfma_f32_16x16x32_bf16 v[110:113], v[130:133], v[198:201], v[110:113]
	v_mfma_f32_16x16x32_bf16 v[106:109], v[138:141], v[198:201], v[106:109]
	v_mfma_f32_16x16x32_bf16 v[94:97], v[130:133], v[206:209], v[94:97]
	v_mfma_f32_16x16x32_bf16 v[90:93], v[138:141], v[206:209], v[90:93]
	v_mfma_f32_16x16x32_bf16 v[78:81], v[130:133], v[214:217], v[78:81]
	v_mfma_f32_16x16x32_bf16 v[74:77], v[138:141], v[214:217], v[74:77]
	v_mfma_f32_16x16x32_bf16 v[126:129], v[134:137], v[194:197], v[126:129]
	v_mfma_f32_16x16x32_bf16 v[122:125], v[142:145], v[194:197], v[122:125]
	v_mfma_f32_16x16x32_bf16 v[110:113], v[134:137], v[202:205], v[110:113]
	v_mfma_f32_16x16x32_bf16 v[106:109], v[142:145], v[202:205], v[106:109]
	v_mfma_f32_16x16x32_bf16 v[94:97], v[134:137], v[210:213], v[94:97]
	v_mfma_f32_16x16x32_bf16 v[90:93], v[142:145], v[210:213], v[90:93]
	v_mfma_f32_16x16x32_bf16 v[78:81], v[134:137], v[218:221], v[78:81]
	v_mfma_f32_16x16x32_bf16 v[74:77], v[142:145], v[218:221], v[74:77]
	s_setprio 0
	s_setprio 1
	v_mfma_f32_16x16x32_bf16 v[118:121], v[146:149], v[190:193], v[118:121]
	v_mfma_f32_16x16x32_bf16 v[114:117], v[164:167], v[190:193], v[114:117]
	v_mfma_f32_16x16x32_bf16 v[102:105], v[146:149], v[198:201], v[102:105]
	v_mfma_f32_16x16x32_bf16 v[98:101], v[164:167], v[198:201], v[98:101]
	v_mfma_f32_16x16x32_bf16 v[86:89], v[146:149], v[206:209], v[86:89]
	v_mfma_f32_16x16x32_bf16 v[82:85], v[164:167], v[206:209], v[82:85]
	v_mfma_f32_16x16x32_bf16 v[70:73], v[146:149], v[214:217], v[70:73]
	v_mfma_f32_16x16x32_bf16 v[66:69], v[164:167], v[214:217], v[66:69]
	v_mfma_f32_16x16x32_bf16 v[118:121], v[150:153], v[194:197], v[118:121]
	v_mfma_f32_16x16x32_bf16 v[114:117], v[180:183], v[194:197], v[114:117]
	v_mfma_f32_16x16x32_bf16 v[102:105], v[150:153], v[202:205], v[102:105]
	v_mfma_f32_16x16x32_bf16 v[98:101], v[180:183], v[202:205], v[98:101]
	v_mfma_f32_16x16x32_bf16 v[86:89], v[150:153], v[210:213], v[86:89]
	v_mfma_f32_16x16x32_bf16 v[82:85], v[180:183], v[210:213], v[82:85]
	v_mfma_f32_16x16x32_bf16 v[70:73], v[150:153], v[218:221], v[70:73]
	v_mfma_f32_16x16x32_bf16 v[66:69], v[180:183], v[218:221], v[66:69]
	s_setprio 0
	s_barrier
; #define PG8_STAGE(bufoff, gbase, voff) do { _Pragma("unroll") for (int _i = 0; _i < 2; ++_i) \
;         __builtin_amdgcn_global_load_lds((const unsigned*)((const char*)(gbase) + (voff)[_i]), (PG8_LAS unsigned*)(lds + (bufoff) + ldsw + _i * 8192), 16, 0, 0); } while (0)
; #define PG8_LDA(dst, b, h) do { _Pragma("unroll") for (int m = 0; m < 4; ++m) _Pragma("unroll") for (int k = 0; k < 2; ++k) dst[m][k] = *(const PG8_LAS bf16x8*)(lds + PG8_SA(b, h) + aoff + m * 2048 + k * 1024); } while (0)
; #define PG8_MMA(ai, bj, At, Bt) do { __builtin_amdgcn_s_setprio(1); _Pragma("unroll") for (int m = 0; m < 4; ++m) _Pragma("unroll") for (int n = 0; n < 2; ++n) _Pragma("unroll") for (int k = 0; k < 2; ++k) \
;         acc[ai][bj][m][n] = __builtin_amdgcn_mfma_f32_16x16x32_bf16(Bt[n][k], At[m][k], acc[ai][bj][m][n], 0, 0, 0); __builtin_amdgcn_s_setprio(0); } while (0)
; #define PG8_WAIT_V(n) asm volatile("s_waitcnt vmcnt(" #n ")" ::: "memory")
; #define PG8_WAIT_L(n) asm volatile("s_waitcnt lgkmcnt(" #n ")" ::: "memory")
; #define PG8_BAR __builtin_amdgcn_s_barrier()
; #define PG8_SCHED __builtin_amdgcn_sched_barrier(0)
; template <class Epi, class Sched, bool ALIGN_EPI = false, bool SP2 = false>
; __device__ __forceinline__ void gemm_phase(PG8_LAS unsigned char* lds, const Gemm g, const Sched& S, const Epi& E) {
;     ...
;             PG8_LDA(At, 1, 1); PG8_STAGE(PG8_SB(1, 0), b3, voffB); PG8_STAGE(PG8_SB(1, 1), b3 + hstep, voffB); PG8_STAGE(PG8_SA(1, 0), a3, voffA);
;             PG8_WAIT_V(8); PG8_WAIT_L(0); PG8_BAR; PG8_MMA(1, 0, At, B0); PG8_MMA(1, 1, At, B1); PG8_BAR; PG8_SCHED;
;     ...
;         }
;         if constexpr (ALIGN_EPI) { if (wr == 0) PG8_BAR; }
	s_add_i32 s27, s27, s82
	v_lshl_add_u64 v[168:169], v[168:169], 0, s[12:13]
	s_mov_b32 m0, s27
	ds_read_b128 v[190:193], v187 offset:49152
	ds_read_b128 v[194:197], v187 offset:50176
	ds_read_b128 v[198:201], v187 offset:51200
	ds_read_b128 v[202:205], v187 offset:52224
	ds_read_b128 v[206:209], v187 offset:53248
	ds_read_b128 v[210:213], v187 offset:54272
	ds_read_b128 v[214:217], v187 offset:55296
	ds_read_b128 v[218:221], v187 offset:56320
	global_load_lds_dwordx4 v[168:169], off
	v_lshl_add_u64 v[168:169], v[222:223], 0, s[12:13]
	s_add_i32 m0, s27, 0x2000
	s_add_i32 s27, s97, s82
	global_load_lds_dwordx4 v[168:169], off
	v_lshl_add_u64 v[168:169], v[232:233], 0, s[12:13]
	s_mov_b32 m0, s27
	s_nop 0
	global_load_lds_dwordx4 v[168:169], off
	v_lshl_add_u64 v[168:169], v[234:235], 0, s[12:13]
	s_add_i32 m0, s27, 0x2000
	s_nop 0
	global_load_lds_dwordx4 v[168:169], off
	v_lshl_add_u64 v[168:169], v[236:237], 0, s[12:13]
	s_mov_b32 m0, s89
	s_nop 0
	global_load_lds_dwordx4 v[168:169], off
	v_lshl_add_u64 v[168:169], v[238:239], 0, s[12:13]
	s_mov_b32 m0, s90
	s_nop 0
	global_load_lds_dwordx4 v[168:169], off
	s_waitcnt vmcnt(8) lgkmcnt(0)
	s_setprio 1
	s_barrier
	v_mfma_f32_16x16x32_bf16 v[62:65], v[130:133], v[190:193], v[62:65]
	v_mfma_f32_16x16x32_bf16 v[58:61], v[138:141], v[190:193], v[58:61]
	v_mfma_f32_16x16x32_bf16 v[46:49], v[130:133], v[198:201], v[46:49]
	v_mfma_f32_16x16x32_bf16 v[42:45], v[138:141], v[198:201], v[42:45]
	v_mfma_f32_16x16x32_bf16 v[30:33], v[130:133], v[206:209], v[30:33]
	v_mfma_f32_16x16x32_bf16 v[26:29], v[138:141], v[206:209], v[26:29]
	v_mfma_f32_16x16x32_bf16 v[14:17], v[130:133], v[214:217], v[14:17]
	v_mfma_f32_16x16x32_bf16 v[10:13], v[138:141], v[214:217], v[10:13]
	v_mfma_f32_16x16x32_bf16 v[62:65], v[134:137], v[194:197], v[62:65]
	v_mfma_f32_16x16x32_bf16 v[58:61], v[142:145], v[194:197], v[58:61]
	v_mfma_f32_16x16x32_bf16 v[46:49], v[134:137], v[202:205], v[46:49]
	v_mfma_f32_16x16x32_bf16 v[42:45], v[142:145], v[202:205], v[42:45]
	v_mfma_f32_16x16x32_bf16 v[30:33], v[134:137], v[210:213], v[30:33]
	v_mfma_f32_16x16x32_bf16 v[26:29], v[142:145], v[210:213], v[26:29]
	v_mfma_f32_16x16x32_bf16 v[14:17], v[134:137], v[218:221], v[14:17]
	v_mfma_f32_16x16x32_bf16 v[10:13], v[142:145], v[218:221], v[10:13]
	s_setprio 0
	s_setprio 1
	v_mfma_f32_16x16x32_bf16 v[54:57], v[146:149], v[190:193], v[54:57]
	v_mfma_f32_16x16x32_bf16 v[50:53], v[164:167], v[190:193], v[50:53]
	v_mfma_f32_16x16x32_bf16 v[38:41], v[146:149], v[198:201], v[38:41]
	v_mfma_f32_16x16x32_bf16 v[34:37], v[164:167], v[198:201], v[34:37]
	v_mfma_f32_16x16x32_bf16 v[22:25], v[146:149], v[206:209], v[22:25]
	v_mfma_f32_16x16x32_bf16 v[18:21], v[164:167], v[206:209], v[18:21]
	v_mfma_f32_16x16x32_bf16 v[6:9], v[146:149], v[214:217], v[6:9]
	v_mfma_f32_16x16x32_bf16 v[2:5], v[164:167], v[214:217], v[2:5]
	v_mfma_f32_16x16x32_bf16 v[54:57], v[150:153], v[194:197], v[54:57]
	v_mfma_f32_16x16x32_bf16 v[50:53], v[180:183], v[194:197], v[50:53]
	v_mfma_f32_16x16x32_bf16 v[38:41], v[150:153], v[202:205], v[38:41]
	v_mfma_f32_16x16x32_bf16 v[34:37], v[180:183], v[202:205], v[34:37]
	v_mfma_f32_16x16x32_bf16 v[22:25], v[150:153], v[210:213], v[22:25]
	v_mfma_f32_16x16x32_bf16 v[18:21], v[180:183], v[210:213], v[18:21]
	v_mfma_f32_16x16x32_bf16 v[6:9], v[150:153], v[218:221], v[6:9]
	v_mfma_f32_16x16x32_bf16 v[2:5], v[180:183], v[218:221], v[2:5]
	s_setprio 0
	s_barrier
	s_add_u32 s44, s44, 0x100
	s_addc_u32 s45, s45, 0
	s_add_u32 s94, s94, 0x100
	s_addc_u32 s95, s95, 0
	s_cmp_ge_u32 s96, s88
	s_mov_b32 s74, s96
	s_cbranch_scc0 .LBB0_1427
	s_and_b64 vcc, exec, s[48:49]
	s_cbranch_vccz .LBB0_1430
	s_barrier

; #define PG8_STAGE(bufoff, gbase, voff) do { _Pragma("unroll") for (int _i = 0; _i < 2; ++_i) \
;         __builtin_amdgcn_global_load_lds((const unsigned*)((const char*)(gbase) + (voff)[_i]), (PG8_LAS unsigned*)(lds + (bufoff) + ldsw + _i * 8192), 16, 0, 0); } while (0)
; #define PG8_LDA(dst, b, h) do { _Pragma("unroll") for (int m = 0; m < 4; ++m) _Pragma("unroll") for (int k = 0; k < 2; ++k) dst[m][k] = *(const PG8_LAS bf16x8*)(lds + PG8_SA(b, h) + aoff + m * 2048 + k * 1024); } while (0)
; #define PG8_LDB(dst, b, h) do { _Pragma("unroll") for (int n = 0; n < 2; ++n) _Pragma("unroll") for (int k = 0; k < 2; ++k) dst[n][k] = *(const PG8_LAS bf16x8*)(lds + PG8_SB(b, h) + boff + n * 2048 + k * 1024); } while (0)
; #define PG8_MMA(ai, bj, At, Bt) do { __builtin_amdgcn_s_setprio(1); _Pragma("unroll") for (int m = 0; m < 4; ++m) _Pragma("unroll") for (int n = 0; n < 2; ++n) _Pragma("unroll") for (int k = 0; k < 2; ++k) \
;         acc[ai][bj][m][n] = __builtin_amdgcn_mfma_f32_16x16x32_bf16(Bt[n][k], At[m][k], acc[ai][bj][m][n], 0, 0, 0); __builtin_amdgcn_s_setprio(0); } while (0)
; #define PG8_WAIT_V(n) asm volatile("s_waitcnt vmcnt(" #n ")" ::: "memory")
; #define PG8_WAIT_L(n) asm volatile("s_waitcnt lgkmcnt(" #n ")" ::: "memory")
; #define PG8_BAR __builtin_amdgcn_s_barrier()
; #define PG8_SCHED __builtin_amdgcn_sched_barrier(0)
; template <class Epi, class Sched, bool ALIGN_EPI = false, bool SP2 = false>
; __device__ __forceinline__ void gemm_phase(PG8_LAS unsigned char* lds, const Gemm g, const Sched& S, const Epi& E) {
;     ...
;         for (int t = 0; t < nt; t += 2) {
;             const bool last = (t == nt - 2);
;             const char* a1 = cA + (size_t)(t + 1) * kstep;
;             const char* a2 = last ? nA : cA + (size_t)(t + 2) * kstep; const char* b2 = last ? nB : cB + (size_t)(t + 2) * kstep;
;             const char* a3 = a2 + kstep; const char* b3 = b2 + kstep;
;             if (last && has_next) S.a_ready(nxt);
;             if constexpr (SP2) {
;             PG8_LDB(B0, 0, 0); PG8_LDB(B1, 0, 1); PG8_SCHED; PG8_LDA(At, 0, 0); PG8_STAGE(PG8_SA(1, 1), a1 + hstep, voffA);
;             PG8_WAIT_V(8); PG8_WAIT_L(0); PG8_BAR; PG8_MMA(0, 0, At, B0); PG8_MMA(0, 1, At, B1); PG8_BAR; PG8_SCHED;
;             PG8_LDA(At, 0, 1); PG8_STAGE(PG8_SB(0, 0), b2, voffB); PG8_STAGE(PG8_SB(0, 1), b2 + hstep, voffB); PG8_STAGE(PG8_SA(0, 0), a2, voffA);
.LBB0_1497:
	s_add_u32 s50, s0, 0xfff80080
	s_addc_u32 s51, s1, -1
	s_add_i32 s81, 0, 0x10000
	s_cmp_eq_u32 s80, 28
	s_cselect_b32 s53, s24, s51
	s_cselect_b32 s52, s25, s50
	s_cselect_b32 s51, s43, s75
	s_cselect_b32 s50, s45, s74
	s_add_i32 s84, 0, 0x14000
	v_add_u32_e32 v152, s81, v160
	v_add_u32_e32 v156, s84, v160
	ds_read_b128 v[140:143], v152
	ds_read_b128 v[144:147], v152 offset:1024
	ds_read_b128 v[148:151], v152 offset:2048
	ds_read_b128 v[152:155], v152 offset:3072
	ds_read_b128 v[164:167], v156
	ds_read_b128 v[180:183], v156 offset:1024
	ds_read_b128 v[184:187], v156 offset:2048
	ds_read_b128 v[190:193], v156 offset:3072
	v_lshl_add_u64 v[156:157], s[0:1], 0, v[136:137]
	s_add_i32 m0, s39, 0xc000
	ds_read_b128 v[194:197], v162
	ds_read_b128 v[198:201], v162 offset:1024
	ds_read_b128 v[202:205], v162 offset:2048
	ds_read_b128 v[206:209], v162 offset:3072
	ds_read_b128 v[210:213], v162 offset:4096
	ds_read_b128 v[214:217], v162 offset:5120
	ds_read_b128 v[218:221], v162 offset:6144
	ds_read_b128 v[232:235], v162 offset:7168
	global_load_lds_dwordx4 v[156:157], off
	v_lshl_add_u64 v[156:157], s[0:1], 0, v[138:139]
	s_add_i32 m0, s39, 0xe000
	s_nop 0
	global_load_lds_dwordx4 v[156:157], off
	s_waitcnt vmcnt(8) lgkmcnt(0)
	s_setprio 1
	s_barrier
	v_mfma_f32_16x16x32_bf16 v[126:129], v[140:143], v[194:197], v[126:129]
	v_mfma_f32_16x16x32_bf16 v[122:125], v[148:151], v[194:197], v[122:125]
	v_mfma_f32_16x16x32_bf16 v[110:113], v[140:143], v[202:205], v[110:113]
	v_mfma_f32_16x16x32_bf16 v[106:109], v[148:151], v[202:205], v[106:109]
	v_mfma_f32_16x16x32_bf16 v[94:97], v[140:143], v[210:213], v[94:97]
	v_mfma_f32_16x16x32_bf16 v[90:93], v[148:151], v[210:213], v[90:93]
	v_mfma_f32_16x16x32_bf16 v[78:81], v[140:143], v[218:221], v[78:81]
	v_mfma_f32_16x16x32_bf16 v[74:77], v[148:151], v[218:221], v[74:77]
	v_mfma_f32_16x16x32_bf16 v[126:129], v[144:147], v[198:201], v[126:129]
	v_mfma_f32_16x16x32_bf16 v[122:125], v[152:155], v[198:201], v[122:125]
	v_mfma_f32_16x16x32_bf16 v[110:113], v[144:147], v[206:209], v[110:113]
	v_mfma_f32_16x16x32_bf16 v[106:109], v[152:155], v[206:209], v[106:109]
	v_mfma_f32_16x16x32_bf16 v[94:97], v[144:147], v[214:217], v[94:97]
	v_mfma_f32_16x16x32_bf16 v[90:93], v[152:155], v[214:217], v[90:93]
	v_mfma_f32_16x16x32_bf16 v[78:81], v[144:147], v[232:235], v[78:81]
	v_mfma_f32_16x16x32_bf16 v[74:77], v[152:155], v[232:235], v[74:77]
	s_setprio 0
	s_setprio 1
	v_mfma_f32_16x16x32_bf16 v[118:121], v[164:167], v[194:197], v[118:121]
	v_mfma_f32_16x16x32_bf16 v[114:117], v[184:187], v[194:197], v[114:117]
	v_mfma_f32_16x16x32_bf16 v[102:105], v[164:167], v[202:205], v[102:105]
	v_mfma_f32_16x16x32_bf16 v[98:101], v[184:187], v[202:205], v[98:101]
	v_mfma_f32_16x16x32_bf16 v[86:89], v[164:167], v[210:213], v[86:89]
	v_mfma_f32_16x16x32_bf16 v[82:85], v[184:187], v[210:213], v[82:85]
	v_mfma_f32_16x16x32_bf16 v[70:73], v[164:167], v[218:221], v[70:73]
	v_mfma_f32_16x16x32_bf16 v[66:69], v[184:187], v[218:221], v[66:69]
	v_mfma_f32_16x16x32_bf16 v[118:121], v[180:183], v[198:201], v[118:121]
	v_mfma_f32_16x16x32_bf16 v[114:117], v[190:193], v[198:201], v[114:117]
	v_mfma_f32_16x16x32_bf16 v[102:105], v[180:183], v[206:209], v[102:105]
	v_mfma_f32_16x16x32_bf16 v[98:101], v[190:193], v[206:209], v[98:101]
	v_mfma_f32_16x16x32_bf16 v[86:89], v[180:183], v[214:217], v[86:89]
	v_mfma_f32_16x16x32_bf16 v[82:85], v[190:193], v[214:217], v[82:85]
	v_mfma_f32_16x16x32_bf16 v[70:73], v[180:183], v[232:235], v[70:73]
	v_mfma_f32_16x16x32_bf16 v[66:69], v[190:193], v[232:235], v[66:69]
	s_setprio 0
	s_barrier
	s_add_i32 s81, s81, s38
	v_lshl_add_u64 v[156:157], s[50:51], 0, v[0:1]
	s_mov_b32 m0, s81
	ds_read_b128 v[194:197], v162 offset:16384
	ds_read_b128 v[198:201], v162 offset:17408
	ds_read_b128 v[202:205], v162 offset:18432
	ds_read_b128 v[206:209], v162 offset:19456
	ds_read_b128 v[210:213], v162 offset:20480
	ds_read_b128 v[214:217], v162 offset:21504
	ds_read_b128 v[218:221], v162 offset:22528
	ds_read_b128 v[232:235], v162 offset:23552
	global_load_lds_dwordx4 v[156:157], off
	s_add_i32 m0, s81, 0x2000
	s_add_u32 s82, s50, 0x80000
	v_lshl_add_u64 v[168:169], s[50:51], 0, v[130:131]
	s_addc_u32 s83, s51, 0
	s_add_i32 s81, s84, s38
	global_load_lds_dwordx4 v[168:169], off
	v_lshl_add_u64 v[222:223], s[82:83], 0, v[0:1]
	s_mov_b32 m0, s81
	v_lshl_add_u64 v[236:237], s[52:53], 0, v[132:133]
	global_load_lds_dwordx4 v[222:223], off
	v_lshl_add_u64 v[222:223], s[82:83], 0, v[130:131]
	s_add_i32 m0, s81, 0x2000
	s_nop 0
	global_load_lds_dwordx4 v[222:223], off
	v_lshl_add_u64 v[222:223], s[52:53], 0, v[134:135]
	s_mov_b32 m0, s39
	s_nop 0
	global_load_lds_dwordx4 v[222:223], off
	s_mov_b32 m0, s58
	s_nop 0
	global_load_lds_dwordx4 v[236:237], off
	s_waitcnt vmcnt(8) lgkmcnt(0)
	s_setprio 1
	s_barrier
; #define PG8_STAGE(bufoff, gbase, voff) do { _Pragma("unroll") for (int _i = 0; _i < 2; ++_i) \
;         __builtin_amdgcn_global_load_lds((const unsigned*)((const char*)(gbase) + (voff)[_i]), (PG8_LAS unsigned*)(lds + (bufoff) + ldsw + _i * 8192), 16, 0, 0); } while (0)
; #define PG8_LDA(dst, b, h) do { _Pragma("unroll") for (int m = 0; m < 4; ++m) _Pragma("unroll") for (int k = 0; k < 2; ++k) dst[m][k] = *(const PG8_LAS bf16x8*)(lds + PG8_SA(b, h) + aoff + m * 2048 + k * 1024); } while (0)
; #define PG8_LDB(dst, b, h) do { _Pragma("unroll") for (int n = 0; n < 2; ++n) _Pragma("unroll") for (int k = 0; k < 2; ++k) dst[n][k] = *(const PG8_LAS bf16x8*)(lds + PG8_SB(b, h) + boff + n * 2048 + k * 1024); } while (0)
; #define PG8_MMA(ai, bj, At, Bt) do { __builtin_amdgcn_s_setprio(1); _Pragma("unroll") for (int m = 0; m < 4; ++m) _Pragma("unroll") for (int n = 0; n < 2; ++n) _Pragma("unroll") for (int k = 0; k < 2; ++k) \
;         acc[ai][bj][m][n] = __builtin_amdgcn_mfma_f32_16x16x32_bf16(Bt[n][k], At[m][k], acc[ai][bj][m][n], 0, 0, 0); __builtin_amdgcn_s_setprio(0); } while (0)
; #define PG8_WAIT_V(n) asm volatile("s_waitcnt vmcnt(" #n ")" ::: "memory")
; #define PG8_WAIT_L(n) asm volatile("s_waitcnt lgkmcnt(" #n ")" ::: "memory")
; #define PG8_BAR __builtin_amdgcn_s_barrier()
; #define PG8_SCHED __builtin_amdgcn_sched_barrier(0)
; template <class Epi, class Sched, bool ALIGN_EPI = false, bool SP2 = false>
; __device__ __forceinline__ void gemm_phase(PG8_LAS unsigned char* lds, const Gemm g, const Sched& S, const Epi& E) {
;     ...
;             PG8_WAIT_V(8); PG8_WAIT_L(0); PG8_BAR; PG8_MMA(1, 0, At, B0); PG8_MMA(1, 1, At, B1); PG8_BAR; PG8_SCHED;
;             PG8_LDB(B0, 1, 0); PG8_LDB(B1, 1, 1); PG8_SCHED; PG8_LDA(At, 1, 0); PG8_STAGE(PG8_SA(0, 1), a2 + hstep, voffA);
;             PG8_WAIT_V(8); PG8_WAIT_L(0); PG8_BAR; PG8_MMA(0, 0, At, B0); PG8_MMA(0, 1, At, B1); PG8_BAR; PG8_SCHED;
	v_mfma_f32_16x16x32_bf16 v[62:65], v[140:143], v[194:197], v[62:65]
	v_mfma_f32_16x16x32_bf16 v[58:61], v[148:151], v[194:197], v[58:61]
	v_mfma_f32_16x16x32_bf16 v[46:49], v[140:143], v[202:205], v[46:49]
	v_mfma_f32_16x16x32_bf16 v[42:45], v[148:151], v[202:205], v[42:45]
	v_mfma_f32_16x16x32_bf16 v[30:33], v[140:143], v[210:213], v[30:33]
	v_mfma_f32_16x16x32_bf16 v[26:29], v[148:151], v[210:213], v[26:29]
	v_mfma_f32_16x16x32_bf16 v[14:17], v[140:143], v[218:221], v[14:17]
	v_mfma_f32_16x16x32_bf16 v[10:13], v[148:151], v[218:221], v[10:13]
	v_mfma_f32_16x16x32_bf16 v[62:65], v[144:147], v[198:201], v[62:65]
	v_mfma_f32_16x16x32_bf16 v[58:61], v[152:155], v[198:201], v[58:61]
	v_mfma_f32_16x16x32_bf16 v[46:49], v[144:147], v[206:209], v[46:49]
	v_mfma_f32_16x16x32_bf16 v[42:45], v[152:155], v[206:209], v[42:45]
	v_mfma_f32_16x16x32_bf16 v[30:33], v[144:147], v[214:217], v[30:33]
	v_mfma_f32_16x16x32_bf16 v[26:29], v[152:155], v[214:217], v[26:29]
	v_mfma_f32_16x16x32_bf16 v[14:17], v[144:147], v[232:235], v[14:17]
	v_mfma_f32_16x16x32_bf16 v[10:13], v[152:155], v[232:235], v[10:13]
	s_setprio 0
	s_setprio 1
	v_mfma_f32_16x16x32_bf16 v[54:57], v[164:167], v[194:197], v[54:57]
	v_mfma_f32_16x16x32_bf16 v[50:53], v[184:187], v[194:197], v[50:53]
	v_mfma_f32_16x16x32_bf16 v[38:41], v[164:167], v[202:205], v[38:41]
	v_mfma_f32_16x16x32_bf16 v[34:37], v[184:187], v[202:205], v[34:37]
	v_mfma_f32_16x16x32_bf16 v[22:25], v[164:167], v[210:213], v[22:25]
	v_mfma_f32_16x16x32_bf16 v[18:21], v[184:187], v[210:213], v[18:21]
	v_mfma_f32_16x16x32_bf16 v[6:9], v[164:167], v[218:221], v[6:9]
	v_mfma_f32_16x16x32_bf16 v[2:5], v[184:187], v[218:221], v[2:5]
	v_mfma_f32_16x16x32_bf16 v[54:57], v[180:183], v[198:201], v[54:57]
	v_mfma_f32_16x16x32_bf16 v[50:53], v[190:193], v[198:201], v[50:53]
	v_mfma_f32_16x16x32_bf16 v[38:41], v[180:183], v[206:209], v[38:41]
	v_mfma_f32_16x16x32_bf16 v[34:37], v[190:193], v[206:209], v[34:37]
	v_mfma_f32_16x16x32_bf16 v[22:25], v[180:183], v[214:217], v[22:25]
	v_mfma_f32_16x16x32_bf16 v[18:21], v[190:193], v[214:217], v[18:21]
	v_mfma_f32_16x16x32_bf16 v[6:9], v[180:183], v[232:235], v[6:9]
	v_mfma_f32_16x16x32_bf16 v[2:5], v[190:193], v[232:235], v[2:5]
	s_setprio 0
	s_barrier
	s_add_i32 s81, 0, 0x18000
	s_add_i32 s82, 0, 0x1c000
	v_add_u32_e32 v152, s81, v160
	v_add_u32_e32 v158, s82, v160
	ds_read_b128 v[140:143], v152
	ds_read_b128 v[144:147], v152 offset:1024
	ds_read_b128 v[148:151], v152 offset:2048
	ds_read_b128 v[152:155], v152 offset:3072
	ds_read_b128 v[164:167], v158
	ds_read_b128 v[180:183], v158 offset:1024
	ds_read_b128 v[184:187], v158 offset:2048
	ds_read_b128 v[190:193], v158 offset:3072
	s_add_u32 s52, s52, 0x80000
	s_addc_u32 s53, s53, 0
	s_mov_b32 m0, s60
	v_lshl_add_u64 v[238:239], s[52:53], 0, v[134:135]
	ds_read_b128 v[194:197], v162 offset:32768
	ds_read_b128 v[198:201], v162 offset:33792
	ds_read_b128 v[202:205], v162 offset:34816
	ds_read_b128 v[206:209], v162 offset:35840
	ds_read_b128 v[210:213], v162 offset:36864
	ds_read_b128 v[214:217], v162 offset:37888
	ds_read_b128 v[218:221], v162 offset:38912
	ds_read_b128 v[232:235], v162 offset:39936
	global_load_lds_dwordx4 v[238:239], off
	v_lshl_add_u64 v[238:239], s[52:53], 0, v[132:133]
	s_mov_b32 m0, s61
	s_nop 0
	global_load_lds_dwordx4 v[238:239], off
	s_waitcnt vmcnt(8) lgkmcnt(0)
	s_setprio 1
	s_barrier
	v_mfma_f32_16x16x32_bf16 v[126:129], v[140:143], v[194:197], v[126:129]
	v_mfma_f32_16x16x32_bf16 v[122:125], v[148:151], v[194:197], v[122:125]
	v_mfma_f32_16x16x32_bf16 v[110:113], v[140:143], v[202:205], v[110:113]
	v_mfma_f32_16x16x32_bf16 v[106:109], v[148:151], v[202:205], v[106:109]
	v_mfma_f32_16x16x32_bf16 v[94:97], v[140:143], v[210:213], v[94:97]
	v_mfma_f32_16x16x32_bf16 v[90:93], v[148:151], v[210:213], v[90:93]
	v_mfma_f32_16x16x32_bf16 v[78:81], v[140:143], v[218:221], v[78:81]
	v_mfma_f32_16x16x32_bf16 v[74:77], v[148:151], v[218:221], v[74:77]
	v_mfma_f32_16x16x32_bf16 v[126:129], v[144:147], v[198:201], v[126:129]
	v_mfma_f32_16x16x32_bf16 v[122:125], v[152:155], v[198:201], v[122:125]
	v_mfma_f32_16x16x32_bf16 v[110:113], v[144:147], v[206:209], v[110:113]
	v_mfma_f32_16x16x32_bf16 v[106:109], v[152:155], v[206:209], v[106:109]
	v_mfma_f32_16x16x32_bf16 v[94:97], v[144:147], v[214:217], v[94:97]
	v_mfma_f32_16x16x32_bf16 v[90:93], v[152:155], v[214:217], v[90:93]
	v_mfma_f32_16x16x32_bf16 v[78:81], v[144:147], v[232:235], v[78:81]
	v_mfma_f32_16x16x32_bf16 v[74:77], v[152:155], v[232:235], v[74:77]
	s_setprio 0
	s_setprio 1
	v_mfma_f32_16x16x32_bf16 v[118:121], v[164:167], v[194:197], v[118:121]
	v_mfma_f32_16x16x32_bf16 v[114:117], v[184:187], v[194:197], v[114:117]
	v_mfma_f32_16x16x32_bf16 v[102:105], v[164:167], v[202:205], v[102:105]
	v_mfma_f32_16x16x32_bf16 v[98:101], v[184:187], v[202:205], v[98:101]
	v_mfma_f32_16x16x32_bf16 v[86:89], v[164:167], v[210:213], v[86:89]
	v_mfma_f32_16x16x32_bf16 v[82:85], v[184:187], v[210:213], v[82:85]
	v_mfma_f32_16x16x32_bf16 v[70:73], v[164:167], v[218:221], v[70:73]
	v_mfma_f32_16x16x32_bf16 v[66:69], v[184:187], v[218:221], v[66:69]
	v_mfma_f32_16x16x32_bf16 v[118:121], v[180:183], v[198:201], v[118:121]
	v_mfma_f32_16x16x32_bf16 v[114:117], v[190:193], v[198:201], v[114:117]
	v_mfma_f32_16x16x32_bf16 v[102:105], v[180:183], v[206:209], v[102:105]
	v_mfma_f32_16x16x32_bf16 v[98:101], v[190:193], v[206:209], v[98:101]
	v_mfma_f32_16x16x32_bf16 v[86:89], v[180:183], v[214:217], v[86:89]
	v_mfma_f32_16x16x32_bf16 v[82:85], v[190:193], v[214:217], v[82:85]
	v_mfma_f32_16x16x32_bf16 v[70:73], v[180:183], v[232:235], v[70:73]
	v_mfma_f32_16x16x32_bf16 v[66:69], v[190:193], v[232:235], v[66:69]
	s_setprio 0
	s_barrier
; #define PG8_STAGE(bufoff, gbase, voff) do { _Pragma("unroll") for (int _i = 0; _i < 2; ++_i) \
;         __builtin_amdgcn_global_load_lds((const unsigned*)((const char*)(gbase) + (voff)[_i]), (PG8_LAS unsigned*)(lds + (bufoff) + ldsw + _i * 8192), 16, 0, 0); } while (0)
; #define PG8_LDA(dst, b, h) do { _Pragma("unroll") for (int m = 0; m < 4; ++m) _Pragma("unroll") for (int k = 0; k < 2; ++k) dst[m][k] = *(const PG8_LAS bf16x8*)(lds + PG8_SA(b, h) + aoff + m * 2048 + k * 1024); } while (0)
; #define PG8_MMA(ai, bj, At, Bt) do { __builtin_amdgcn_s_setprio(1); _Pragma("unroll") for (int m = 0; m < 4; ++m) _Pragma("unroll") for (int n = 0; n < 2; ++n) _Pragma("unroll") for (int k = 0; k < 2; ++k) \
;         acc[ai][bj][m][n] = __builtin_amdgcn_mfma_f32_16x16x32_bf16(Bt[n][k], At[m][k], acc[ai][bj][m][n], 0, 0, 0); __builtin_amdgcn_s_setprio(0); } while (0)
; #define PG8_WAIT_V(n) asm volatile("s_waitcnt vmcnt(" #n ")" ::: "memory")
; #define PG8_WAIT_L(n) asm volatile("s_waitcnt lgkmcnt(" #n ")" ::: "memory")
; #define PG8_BAR __builtin_amdgcn_s_barrier()
; #define PG8_SCHED __builtin_amdgcn_sched_barrier(0)
; template <class Epi, class Sched, bool ALIGN_EPI = false, bool SP2 = false>
; __device__ __forceinline__ void gemm_phase(PG8_LAS unsigned char* lds, const Gemm g, const Sched& S, const Epi& E) {
;     ...
;             PG8_LDA(At, 1, 1); PG8_STAGE(PG8_SB(1, 0), b3, voffB); PG8_STAGE(PG8_SB(1, 1), b3 + hstep, voffB); PG8_STAGE(PG8_SA(1, 0), a3, voffA);
;             PG8_WAIT_V(8); PG8_WAIT_L(0); PG8_BAR; PG8_MMA(1, 0, At, B0); PG8_MMA(1, 1, At, B1); PG8_BAR; PG8_SCHED;
;     ...
;         }
;         if constexpr (ALIGN_EPI) { if (wr == 0) PG8_BAR; }
	s_add_i32 s52, s81, s38
	v_lshl_add_u64 v[156:157], v[156:157], 0, s[12:13]
	s_mov_b32 m0, s52
	ds_read_b128 v[194:197], v162 offset:49152
	ds_read_b128 v[198:201], v162 offset:50176
	ds_read_b128 v[202:205], v162 offset:51200
	ds_read_b128 v[206:209], v162 offset:52224
	ds_read_b128 v[210:213], v162 offset:53248
	ds_read_b128 v[214:217], v162 offset:54272
	ds_read_b128 v[218:221], v162 offset:55296
	ds_read_b128 v[232:235], v162 offset:56320
	global_load_lds_dwordx4 v[156:157], off
	s_add_i32 m0, s52, 0x2000
	s_add_u32 s50, s50, 0x80080
	v_lshl_add_u64 v[156:157], v[168:169], 0, s[12:13]
	s_addc_u32 s51, s51, 0
	s_add_i32 s52, s82, s38
	global_load_lds_dwordx4 v[156:157], off
	v_lshl_add_u64 v[156:157], s[50:51], 0, v[0:1]
	s_mov_b32 m0, s52
	s_nop 0
	global_load_lds_dwordx4 v[156:157], off
	v_lshl_add_u64 v[156:157], s[50:51], 0, v[130:131]
	s_add_i32 m0, s52, 0x2000
	s_nop 0
	global_load_lds_dwordx4 v[156:157], off
	v_lshl_add_u64 v[156:157], v[222:223], 0, s[12:13]
	s_mov_b32 m0, s62
	s_nop 0
	global_load_lds_dwordx4 v[156:157], off
	v_lshl_add_u64 v[156:157], v[236:237], 0, s[12:13]
	s_mov_b32 m0, s63
	s_nop 0
	global_load_lds_dwordx4 v[156:157], off
	s_waitcnt vmcnt(8) lgkmcnt(0)
	s_setprio 1
	s_barrier
	v_mfma_f32_16x16x32_bf16 v[62:65], v[140:143], v[194:197], v[62:65]
	v_mfma_f32_16x16x32_bf16 v[58:61], v[148:151], v[194:197], v[58:61]
	v_mfma_f32_16x16x32_bf16 v[46:49], v[140:143], v[202:205], v[46:49]
	v_mfma_f32_16x16x32_bf16 v[42:45], v[148:151], v[202:205], v[42:45]
	v_mfma_f32_16x16x32_bf16 v[30:33], v[140:143], v[210:213], v[30:33]
	v_mfma_f32_16x16x32_bf16 v[26:29], v[148:151], v[210:213], v[26:29]
	v_mfma_f32_16x16x32_bf16 v[14:17], v[140:143], v[218:221], v[14:17]
	v_mfma_f32_16x16x32_bf16 v[10:13], v[148:151], v[218:221], v[10:13]
	v_mfma_f32_16x16x32_bf16 v[62:65], v[144:147], v[198:201], v[62:65]
	v_mfma_f32_16x16x32_bf16 v[58:61], v[152:155], v[198:201], v[58:61]
	v_mfma_f32_16x16x32_bf16 v[46:49], v[144:147], v[206:209], v[46:49]
	v_mfma_f32_16x16x32_bf16 v[42:45], v[152:155], v[206:209], v[42:45]
	v_mfma_f32_16x16x32_bf16 v[30:33], v[144:147], v[214:217], v[30:33]
	v_mfma_f32_16x16x32_bf16 v[26:29], v[152:155], v[214:217], v[26:29]
	v_mfma_f32_16x16x32_bf16 v[14:17], v[144:147], v[232:235], v[14:17]
	v_mfma_f32_16x16x32_bf16 v[10:13], v[152:155], v[232:235], v[10:13]
	s_setprio 0
	s_setprio 1
	v_mfma_f32_16x16x32_bf16 v[54:57], v[164:167], v[194:197], v[54:57]
	v_mfma_f32_16x16x32_bf16 v[50:53], v[184:187], v[194:197], v[50:53]
	v_mfma_f32_16x16x32_bf16 v[38:41], v[164:167], v[202:205], v[38:41]
	v_mfma_f32_16x16x32_bf16 v[34:37], v[184:187], v[202:205], v[34:37]
	v_mfma_f32_16x16x32_bf16 v[22:25], v[164:167], v[210:213], v[22:25]
	v_mfma_f32_16x16x32_bf16 v[18:21], v[184:187], v[210:213], v[18:21]
	v_mfma_f32_16x16x32_bf16 v[6:9], v[164:167], v[218:221], v[6:9]
	v_mfma_f32_16x16x32_bf16 v[2:5], v[184:187], v[218:221], v[2:5]
	v_mfma_f32_16x16x32_bf16 v[54:57], v[180:183], v[198:201], v[54:57]
	v_mfma_f32_16x16x32_bf16 v[50:53], v[190:193], v[198:201], v[50:53]
	v_mfma_f32_16x16x32_bf16 v[38:41], v[180:183], v[206:209], v[38:41]
	v_mfma_f32_16x16x32_bf16 v[34:37], v[190:193], v[206:209], v[34:37]
	v_mfma_f32_16x16x32_bf16 v[22:25], v[180:183], v[214:217], v[22:25]
	v_mfma_f32_16x16x32_bf16 v[18:21], v[190:193], v[214:217], v[18:21]
	v_mfma_f32_16x16x32_bf16 v[6:9], v[180:183], v[232:235], v[6:9]
	v_mfma_f32_16x16x32_bf16 v[2:5], v[190:193], v[232:235], v[2:5]
	s_setprio 0
	s_barrier
	s_add_i32 s80, s80, 2
	s_add_u32 s0, s0, 0x100
	s_addc_u32 s1, s1, 0
	s_add_u32 s74, s74, 0x100
	s_addc_u32 s75, s75, 0
	s_cmp_gt_u32 s80, 29
	s_cbranch_scc0 .LBB0_1497
	s_and_b64 vcc, exec, s[30:31]
	s_cbranch_vccz .LBB0_1500
	s_barrier
